# attention: hipcc's 720-instruction if-converted band-mask block replaced by 64-VALU hand-written mask, applied only on the diagonal sub-tile (off-diagonal sub-tiles of masked key tiles are fully valid
# speedup vs baseline: 1.0197x; 1.0197x over previous
; #define LAS __attribute__((address_space(3)))
; #define MFMA32(a, b, c) __builtin_amdgcn_mfma_f32_32x32x16_bf16((a), (b), (c), 0, 0, 0)
; __device__ __forceinline__ void attn_phase(LAS unsigned char* lds, const bf16_t* QKVZ, bf16_t* AO, const float* sink) {
;     ...
;                 if ((mode == 1 && sub < qh) || (mode == 2 && sub > qh)) continue;
;                 f32x16 S[2][2];
; #pragma unroll
;                 for (int kt = 0; kt < 2; ++kt)
; #pragma unroll
;                     for (int qt = 0; qt < 2; ++qt)
; #pragma unroll
;                         for (int i = 0; i < 16; ++i) S[kt][qt][i] = -m_[qt];
; #pragma unroll
;                 for (int kt = 0; kt < 2; ++kt)
; #pragma unroll
;                     for (int ks = 0; ks < 4; ++ks) {
;                         const bf16x8 Kf = *(const LAS bf16x8*)(Ks + (64 * sub + 32 * kt + ql) * KS_PITCH + (16 * ks + 8 * hh) * 2);
;                         S[kt][0] = MFMA32(Kf, Qf[0][ks], S[kt][0]);
;                         S[kt][1] = MFMA32(Kf, Qf[1][ks], S[kt][1]);
;                     }
;                 if (mode) {
; #pragma unroll
;                     for (int kt = 0; kt < 2; ++kt)
; #pragma unroll
;                         for (int qt = 0; qt < 2; ++qt)
; #pragma unroll
;                             for (int i = 0; i < 16; ++i) {
;                                 const int j = 64 * sub + 32 * kt + 8 * (i >> 2) + 4 * hh + (i & 3), iq = 64 * qh + 32 * qt + ql;
;                                 const bool valid = (mode == 1) ? (j >= iq) : (j <= iq);
;                                 S[kt][qt][i] = valid ? S[kt][qt][i] : -1e30f;
;                             }
.LBB0_311:
	s_cmp_lt_i32 s75, s58
	s_cselect_b64 s[0:1], -1, 0
	s_and_b64 s[0:1], s[2:3], s[0:1]
	s_cmp_gt_i32 s75, s58
	s_cselect_b64 s[76:77], -1, 0
	s_and_b64 s[76:77], s[48:49], s[76:77]
	s_or_b64 s[0:1], s[0:1], s[76:77]
	s_and_b64 vcc, exec, s[0:1]
	s_cbranch_vccnz .LBB0_310
	s_lshl_b32 s0, s75, 6
	v_or_b32_e32 v6, s0, v193
	v_mad_u32_u24 v6, v6, s61, v10
	ds_read_b128 v[12:15], v6
	ds_read_b128 v[228:231], v6 offset:32
	v_xor_b32_e32 v96, 0x80000000, v9
	v_xor_b32_e32 v80, 0x80000000, v7
	v_mov_b32_e32 v97, v96
	v_mov_b32_e32 v98, v96
	v_mov_b32_e32 v99, v96
	v_mov_b32_e32 v100, v96
	v_mov_b32_e32 v101, v96
	v_mov_b32_e32 v102, v96
	v_mov_b32_e32 v103, v96
	v_mov_b32_e32 v104, v96
	v_mov_b32_e32 v105, v96
	v_mov_b32_e32 v106, v96
	v_mov_b32_e32 v107, v96
	v_mov_b32_e32 v108, v96
	v_mov_b32_e32 v109, v96
	v_mov_b32_e32 v110, v96
	v_mov_b32_e32 v111, v96
	v_mov_b32_e32 v81, v80
	v_mov_b32_e32 v82, v80
	v_mov_b32_e32 v83, v80
	v_mov_b32_e32 v84, v80
	v_mov_b32_e32 v85, v80
	v_mov_b32_e32 v86, v80
	v_mov_b32_e32 v87, v80
	v_mov_b32_e32 v88, v80
	v_mov_b32_e32 v89, v80
	v_mov_b32_e32 v90, v80
	v_mov_b32_e32 v91, v80
	v_mov_b32_e32 v92, v80
	v_mov_b32_e32 v93, v80
	v_mov_b32_e32 v94, v80
	v_mov_b32_e32 v95, v80
	s_waitcnt lgkmcnt(1)
	v_mfma_f32_32x32x16_bf16 v[128:143], v[12:15], v[144:147], v[96:111]
	s_andn2_b64 vcc, exec, s[50:51]
	v_mfma_f32_32x32x16_bf16 v[112:127], v[12:15], v[160:163], v[80:95]
	s_waitcnt lgkmcnt(0)
	v_mfma_f32_32x32x16_bf16 v[128:143], v[228:231], v[148:151], v[128:143]
	v_mfma_f32_32x32x16_bf16 v[112:127], v[228:231], v[164:167], v[112:127]
	ds_read_b128 v[12:15], v6 offset:64
	ds_read_b128 v[228:231], v6 offset:96
	s_waitcnt lgkmcnt(1)
	v_mfma_f32_32x32x16_bf16 v[128:143], v[12:15], v[152:155], v[128:143]
	v_mfma_f32_32x32x16_bf16 v[112:127], v[12:15], v[168:171], v[112:127]
	s_waitcnt lgkmcnt(0)
	v_mfma_f32_32x32x16_bf16 v[128:143], v[228:231], v[156:159], v[128:143]
	v_mfma_f32_32x32x16_bf16 v[112:127], v[228:231], v[172:175], v[112:127]
	ds_read_b128 v[12:15], v6 offset:4608
	ds_read_b128 v[228:231], v6 offset:4640
	s_waitcnt lgkmcnt(1)
	v_mfma_f32_32x32x16_bf16 v[96:111], v[12:15], v[144:147], v[96:111]
	v_mfma_f32_32x32x16_bf16 v[80:95], v[12:15], v[160:163], v[80:95]
	s_waitcnt lgkmcnt(0)
	v_mfma_f32_32x32x16_bf16 v[96:111], v[228:231], v[148:151], v[96:111]
	v_mfma_f32_32x32x16_bf16 v[80:95], v[228:231], v[164:167], v[80:95]
	ds_read_b128 v[12:15], v6 offset:4672
	ds_read_b128 v[228:231], v6 offset:4704
	s_waitcnt lgkmcnt(1)
	v_mfma_f32_32x32x16_bf16 v[96:111], v[12:15], v[152:155], v[96:111]
	v_mfma_f32_32x32x16_bf16 v[80:95], v[12:15], v[168:171], v[80:95]
	s_waitcnt lgkmcnt(0)
	v_mfma_f32_32x32x16_bf16 v[96:111], v[228:231], v[156:159], v[96:111]
	v_mfma_f32_32x32x16_bf16 v[80:95], v[228:231], v[172:175], v[80:95]
	s_cbranch_vccnz .LBB0_314
	s_cmp_lg_u32 s75, s58
	s_cbranch_scc1 .LBB0_314
	v_or_b32_e32 v6, s0, v214
	v_sub_u32_e32 v8, v215, v6
	s_and_b64 vcc, exec, s[2:3]
	s_nop 4
	s_cbranch_vccz .Lattn_mask_m2
	v_cmp_ge_i32_e64 s[0:1], 0, v8
	v_cmp_ge_i32_e64 s[96:97], 1, v8
	v_cmp_ge_i32_e64 s[98:99], 2, v8
	v_cmp_ge_i32_e64 s[100:101], 3, v8
	v_cndmask_b32_e64 v128, v226, v128, s[0:1]
	v_cndmask_b32_e64 v80, v226, v80, s[0:1]
	v_cndmask_b32_e64 v129, v226, v129, s[96:97]
	v_cndmask_b32_e64 v81, v226, v81, s[96:97]
	v_cndmask_b32_e64 v130, v226, v130, s[98:99]
	v_cndmask_b32_e64 v82, v226, v82, s[98:99]
	v_cndmask_b32_e64 v131, v226, v131, s[100:101]
	v_cndmask_b32_e64 v83, v226, v83, s[100:101]
	v_cmp_ge_i32_e64 s[0:1], 8, v8
	v_cmp_ge_i32_e64 s[96:97], 9, v8
	v_cmp_ge_i32_e64 s[98:99], 10, v8
	v_cmp_ge_i32_e64 s[100:101], 11, v8
	v_cndmask_b32_e64 v132, v226, v132, s[0:1]
	v_cndmask_b32_e64 v84, v226, v84, s[0:1]
	v_cndmask_b32_e64 v133, v226, v133, s[96:97]
	v_cndmask_b32_e64 v85, v226, v85, s[96:97]
	v_cndmask_b32_e64 v134, v226, v134, s[98:99]
	v_cndmask_b32_e64 v86, v226, v86, s[98:99]
	v_cndmask_b32_e64 v135, v226, v135, s[100:101]
	v_cndmask_b32_e64 v87, v226, v87, s[100:101]
	v_cmp_ge_i32_e64 s[0:1], 16, v8
	v_cmp_ge_i32_e64 s[96:97], 17, v8
	v_cmp_ge_i32_e64 s[98:99], 18, v8
	v_cmp_ge_i32_e64 s[100:101], 19, v8
	v_cndmask_b32_e64 v136, v226, v136, s[0:1]
	v_cndmask_b32_e64 v88, v226, v88, s[0:1]
	v_cndmask_b32_e64 v137, v226, v137, s[96:97]
	v_cndmask_b32_e64 v89, v226, v89, s[96:97]
	v_cndmask_b32_e64 v138, v226, v138, s[98:99]
	v_cndmask_b32_e64 v90, v226, v90, s[98:99]
	v_cndmask_b32_e64 v139, v226, v139, s[100:101]
	v_cndmask_b32_e64 v91, v226, v91, s[100:101]
	v_cmp_ge_i32_e64 s[0:1], 24, v8
	v_cmp_ge_i32_e64 s[96:97], 25, v8
	v_cmp_ge_i32_e64 s[98:99], 26, v8
	v_cmp_ge_i32_e64 s[100:101], 27, v8
	v_cndmask_b32_e64 v140, v226, v140, s[0:1]
	v_cndmask_b32_e64 v92, v226, v92, s[0:1]
	v_cndmask_b32_e64 v141, v226, v141, s[96:97]
	v_cndmask_b32_e64 v93, v226, v93, s[96:97]
	v_cndmask_b32_e64 v142, v226, v142, s[98:99]
	v_cndmask_b32_e64 v94, v226, v94, s[98:99]
	v_cndmask_b32_e64 v143, v226, v143, s[100:101]
	v_cndmask_b32_e64 v95, v226, v95, s[100:101]
	v_mov_b32_e32 v112, v226
	v_mov_b32_e32 v113, v226
	v_mov_b32_e32 v114, v226
	v_mov_b32_e32 v115, v226
	v_mov_b32_e32 v116, v226
	v_mov_b32_e32 v117, v226
	v_mov_b32_e32 v118, v226
	v_mov_b32_e32 v119, v226
	v_mov_b32_e32 v120, v226
	v_mov_b32_e32 v121, v226
	v_mov_b32_e32 v122, v226
	v_mov_b32_e32 v123, v226
	v_mov_b32_e32 v124, v226
	v_mov_b32_e32 v125, v226
	v_mov_b32_e32 v126, v226
	v_mov_b32_e32 v127, v226
	s_branch .LBB0_314
; __device__ __forceinline__ void attn_phase(LAS unsigned char* lds, const bf16_t* QKVZ, bf16_t* AO, const float* sink) {
;     ...
;                 if (mode) {
; #pragma unroll
;                     for (int kt = 0; kt < 2; ++kt)
; #pragma unroll
;                         for (int qt = 0; qt < 2; ++qt)
; #pragma unroll
;                             for (int i = 0; i < 16; ++i) {
;                                 const int j = 64 * sub + 32 * kt + 8 * (i >> 2) + 4 * hh + (i & 3), iq = 64 * qh + 32 * qt + ql;
;                                 const bool valid = (mode == 1) ? (j >= iq) : (j <= iq);
;                                 S[kt][qt][i] = valid ? S[kt][qt][i] : -1e30f;
;                             }
.Lattn_mask_m2:
	v_cmp_le_i32_e64 s[0:1], 0, v8
	v_cmp_le_i32_e64 s[96:97], 1, v8
	v_cmp_le_i32_e64 s[98:99], 2, v8
	v_cmp_le_i32_e64 s[100:101], 3, v8
	v_cndmask_b32_e64 v128, v226, v128, s[0:1]
	v_cndmask_b32_e64 v80, v226, v80, s[0:1]
	v_cndmask_b32_e64 v129, v226, v129, s[96:97]
	v_cndmask_b32_e64 v81, v226, v81, s[96:97]
	v_cndmask_b32_e64 v130, v226, v130, s[98:99]
	v_cndmask_b32_e64 v82, v226, v82, s[98:99]
	v_cndmask_b32_e64 v131, v226, v131, s[100:101]
	v_cndmask_b32_e64 v83, v226, v83, s[100:101]
	v_cmp_le_i32_e64 s[0:1], 8, v8
	v_cmp_le_i32_e64 s[96:97], 9, v8
	v_cmp_le_i32_e64 s[98:99], 10, v8
	v_cmp_le_i32_e64 s[100:101], 11, v8
	v_cndmask_b32_e64 v132, v226, v132, s[0:1]
	v_cndmask_b32_e64 v84, v226, v84, s[0:1]
	v_cndmask_b32_e64 v133, v226, v133, s[96:97]
	v_cndmask_b32_e64 v85, v226, v85, s[96:97]
	v_cndmask_b32_e64 v134, v226, v134, s[98:99]
	v_cndmask_b32_e64 v86, v226, v86, s[98:99]
	v_cndmask_b32_e64 v135, v226, v135, s[100:101]
	v_cndmask_b32_e64 v87, v226, v87, s[100:101]
	v_cmp_le_i32_e64 s[0:1], 16, v8
	v_cmp_le_i32_e64 s[96:97], 17, v8
	v_cmp_le_i32_e64 s[98:99], 18, v8
	v_cmp_le_i32_e64 s[100:101], 19, v8
	v_cndmask_b32_e64 v136, v226, v136, s[0:1]
	v_cndmask_b32_e64 v88, v226, v88, s[0:1]
	v_cndmask_b32_e64 v137, v226, v137, s[96:97]
	v_cndmask_b32_e64 v89, v226, v89, s[96:97]
	v_cndmask_b32_e64 v138, v226, v138, s[98:99]
	v_cndmask_b32_e64 v90, v226, v90, s[98:99]
	v_cndmask_b32_e64 v139, v226, v139, s[100:101]
	v_cndmask_b32_e64 v91, v226, v91, s[100:101]
	v_cmp_le_i32_e64 s[0:1], 24, v8
	v_cmp_le_i32_e64 s[96:97], 25, v8
	v_cmp_le_i32_e64 s[98:99], 26, v8
	v_cmp_le_i32_e64 s[100:101], 27, v8
	v_cndmask_b32_e64 v140, v226, v140, s[0:1]
	v_cndmask_b32_e64 v92, v226, v92, s[0:1]
	v_cndmask_b32_e64 v141, v226, v141, s[96:97]
	v_cndmask_b32_e64 v93, v226, v93, s[96:97]
	v_cndmask_b32_e64 v142, v226, v142, s[98:99]
	v_cndmask_b32_e64 v94, v226, v94, s[98:99]
	v_cndmask_b32_e64 v143, v226, v143, s[100:101]
	v_cndmask_b32_e64 v95, v226, v95, s[100:101]
	v_mov_b32_e32 v96, v226
	v_mov_b32_e32 v97, v226
	v_mov_b32_e32 v98, v226
	v_mov_b32_e32 v99, v226
	v_mov_b32_e32 v100, v226
	v_mov_b32_e32 v101, v226
	v_mov_b32_e32 v102, v226
	v_mov_b32_e32 v103, v226
	v_mov_b32_e32 v104, v226
	v_mov_b32_e32 v105, v226
	v_mov_b32_e32 v106, v226
	v_mov_b32_e32 v107, v226
	v_mov_b32_e32 v108, v226
	v_mov_b32_e32 v109, v226
	v_mov_b32_e32 v110, v226
	v_mov_b32_e32 v111, v226

; #define LAS __attribute__((address_space(3)))
; template <class Epi>
; __device__ __forceinline__ void gemm64_tile(LAS unsigned char* lds, const bf16_t* A, const bf16_t* Bt, const Epi& E) {
;     constexpr int K = 1024, BK = 128, PITCH = BK * 2 + 16, NKT = K / BK;
;     const int tid = threadIdx.x, lane = tid & 63, wave = __builtin_amdgcn_readfirstlane(tid >> 6), fr = lane & 15, fq = lane >> 4, wr = wave >> 1, wc = wave & 1;
;     LAS unsigned char* As = lds; LAS unsigned char* Bs = lds + 64 * PITCH;
;     const int srow = tid >> 4, sch = tid & 15;
;     const bf16_t* ga = A + (size_t)srow * K + sch * 8; const bf16_t* gb = Bt + (size_t)srow * K + sch * 8;
;     u32x4 ra[2], rb[2];
; #pragma unroll
;     for (int i = 0; i < 2; ++i) { ra[i] = *(const u32x4*)(ga + (size_t)(32 * i) * K); rb[i] = *(const u32x4*)(gb + (size_t)(32 * i) * K); }
;     f32x4 acc[2] = {(f32x4){0.f, 0.f, 0.f, 0.f}, (f32x4){0.f, 0.f, 0.f, 0.f}};
;     for (int kt = 0; kt < NKT; ++kt) {
;         __syncthreads();
; #pragma unroll
;         for (int i = 0; i < 2; ++i) { *(LAS u32x4*)(As + (srow + 32 * i) * PITCH + sch * 16) = ra[i]; *(LAS u32x4*)(Bs + (srow + 32 * i) * PITCH + sch * 16) = rb[i]; }
;         __syncthreads();
;         if (kt + 1 < NKT) {
; #pragma unroll
;             for (int i = 0; i < 2; ++i) { ra[i] = *(const u32x4*)(ga + (size_t)(32 * i) * K + (kt + 1) * BK); rb[i] = *(const u32x4*)(gb + (size_t)(32 * i) * K + (kt + 1) * BK); }
;         }
; #pragma unroll
;         for (int ks = 0; ks < 4; ++ks) {
;             const bf16x8 Af = *(const LAS bf16x8*)(As + (16 * wr + fr) * PITCH + (32 * ks + 8 * fq) * 2);
; #pragma unroll
;             for (int n = 0; n < 2; ++n) {
;                 const bf16x8 Bf = *(const LAS bf16x8*)(Bs + (32 * wc + 16 * n + fr) * PITCH + (32 * ks + 8 * fq) * 2);
;                 acc[n] = __builtin_amdgcn_mfma_f32_16x16x32_bf16(Bf, Af, acc[n], 0, 0, 0);
.LBB0_588:
	s_cmpk_gt_i32 s12, 0xff
	s_cbranch_scc1 .LBB0_590
	s_lshl_b32 s2, s12, 2
	s_andn2_b32 s2, s2, 63
	s_add_i32 s4, s2, 0x4000
	s_ashr_i32 s5, s4, 31
	s_and_b32 s8, s12, 15
	s_lshl_b64 s[2:3], s[4:5], 12
	s_add_u32 s2, s18, s2
	s_addc_u32 s3, s19, s3
	s_lshl_b32 s9, s8, 7
	s_add_u32 s2, s2, s9
	s_addc_u32 s3, s3, 0
	s_lshl_b64 s[4:5], s[4:5], 11
	s_add_u32 s4, s16, s4
	v_lshrrev_b32_e32 v30, 4, v192
	s_addc_u32 s5, s17, s5
	s_lshl_b32 s8, s8, 17
	s_waitcnt vmcnt(0)
	v_lshlrev_b32_e32 v0, 11, v30
	v_mov_b32_e32 v1, 0
	s_add_u32 s8, s52, s8
	v_lshl_add_u64 v[2:3], s[4:5], 0, v[0:1]
	v_lshlrev_b32_e32 v28, 4, v146
	v_mov_b32_e32 v29, v1
	s_addc_u32 s9, s53, 0
	v_lshl_add_u64 v[4:5], v[2:3], 0, v[28:29]
	s_mov_b32 s4, 0x10000
	v_lshl_add_u64 v[2:3], s[8:9], 0, v[0:1]
	v_add_co_u32_e32 v6, vcc, s4, v4
	v_lshl_add_u64 v[8:9], v[2:3], 0, v[28:29]
	global_load_dwordx4 v[12:15], v[4:5], off
	global_load_dwordx4 v[16:19], v[8:9], off
	v_addc_co_u32_e32 v7, vcc, 0, v5, vcc
	global_load_dwordx4 v[20:23], v[6:7], off
	v_add_co_u32_e32 v10, vcc, s4, v8
	v_readfirstlane_b32 s4, v192
	s_nop 0
	v_addc_co_u32_e32 v11, vcc, 0, v9, vcc
	global_load_dwordx4 v[24:27], v[10:11], off
	s_lshr_b32 s8, s4, 3
	s_lshr_b32 s4, s4, 1
	v_bfe_u32 v56, v192, 4, 2
	s_and_b32 s4, s4, 32
	s_movk_i32 s5, 0x110
	v_lshl_add_u32 v2, v56, 4, 0
	v_mul_u32_u24_e32 v0, 0x110, v30
	v_or_b32_e32 v3, s4, v146
	v_add3_u32 v57, 0, v28, v0
	v_mad_u32_u24 v58, v3, s5, v2
	s_barrier
	s_and_b32 s8, s8, 0x1ffffff0
	v_or_b32_e32 v0, s8, v146
	v_mad_u64_u32 v[2:3], s[8:9], v0, s5, v[2:3]
	s_mov_b32 s5, 0
	s_lshl_b32 s4, s4, 1
	s_waitcnt vmcnt(3)
	ds_write_b128 v57, v[12:15]
	s_waitcnt vmcnt(1)
	ds_write_b128 v57, v[20:23] offset:8704
	ds_write_b128 v57, v[16:19] offset:17408
	s_waitcnt vmcnt(0)
	ds_write_b128 v57, v[24:27] offset:26112
	s_waitcnt lgkmcnt(0)
	s_barrier
	ds_read_b128 v[12:15], v58 offset:17408
	ds_read_b128 v[16:19], v58 offset:21760
	ds_read_b128 v[20:23], v2
	ds_read_b128 v[24:27], v2 offset:64
	ds_read_b128 v[28:31], v58 offset:17472
	s_waitcnt lgkmcnt(2)
	v_mfma_f32_16x16x32_bf16 v[12:15], v[12:15], v[20:23], 0
	global_load_dwordx4 v[32:35], v[8:9], off offset:256
	global_load_dwordx4 v[36:39], v[4:5], off offset:256
	ds_read_b128 v[40:43], v58 offset:21824
	v_mfma_f32_16x16x32_bf16 v[16:19], v[16:19], v[20:23], 0
	global_load_dwordx4 v[20:23], v[6:7], off offset:256
	global_load_dwordx4 v[44:47], v[10:11], off offset:256
	s_waitcnt lgkmcnt(1)
	v_mfma_f32_16x16x32_bf16 v[12:15], v[28:31], v[24:27], v[12:15]
	ds_read_b128 v[28:31], v58 offset:17536
	s_waitcnt lgkmcnt(1)
	v_mfma_f32_16x16x32_bf16 v[16:19], v[40:43], v[24:27], v[16:19]
	ds_read_b128 v[24:27], v2 offset:128
	ds_read_b128 v[40:43], v2 offset:192
	ds_read_b128 v[48:51], v58 offset:17600
	s_waitcnt lgkmcnt(2)
	v_mfma_f32_16x16x32_bf16 v[12:15], v[28:31], v[24:27], v[12:15]
	ds_read_b128 v[28:31], v58 offset:21888
	ds_read_b128 v[52:55], v58 offset:21952
	s_waitcnt lgkmcnt(0)
	s_barrier
	v_mfma_f32_16x16x32_bf16 v[16:19], v[28:31], v[24:27], v[16:19]
	s_waitcnt vmcnt(2)
	ds_write_b128 v57, v[36:39]
	ds_write_b128 v57, v[32:35] offset:17408
	s_waitcnt vmcnt(1)
	ds_write_b128 v57, v[20:23] offset:8704
	s_waitcnt vmcnt(0)
	ds_write_b128 v57, v[44:47] offset:26112
	s_waitcnt lgkmcnt(0)
	s_barrier
	ds_read_b128 v[20:23], v58 offset:17408
	v_mfma_f32_16x16x32_bf16 v[12:15], v[48:51], v[40:43], v[12:15]
	ds_read_b128 v[24:27], v58 offset:21760
	ds_read_b128 v[28:31], v2
	ds_read_b128 v[32:35], v2 offset:64
	ds_read_b128 v[36:39], v58 offset:17472
	v_mfma_f32_16x16x32_bf16 v[16:19], v[52:55], v[40:43], v[16:19]
	s_waitcnt lgkmcnt(2)
	v_mfma_f32_16x16x32_bf16 v[12:15], v[20:23], v[28:31], v[12:15]
	global_load_dwordx4 v[20:23], v[8:9], off offset:512
	global_load_dwordx4 v[40:43], v[4:5], off offset:512
	ds_read_b128 v[44:47], v58 offset:21824
	v_mfma_f32_16x16x32_bf16 v[16:19], v[24:27], v[28:31], v[16:19]
	global_load_dwordx4 v[24:27], v[6:7], off offset:512
	global_load_dwordx4 v[28:31], v[10:11], off offset:512
	s_waitcnt lgkmcnt(1)
	v_mfma_f32_16x16x32_bf16 v[12:15], v[36:39], v[32:35], v[12:15]
	ds_read_b128 v[36:39], v58 offset:17536
	s_waitcnt lgkmcnt(1)
	v_mfma_f32_16x16x32_bf16 v[16:19], v[44:47], v[32:35], v[16:19]
	ds_read_b128 v[32:35], v2 offset:128
	ds_read_b128 v[44:47], v2 offset:192
	ds_read_b128 v[48:51], v58 offset:17600
	s_waitcnt lgkmcnt(2)
	v_mfma_f32_16x16x32_bf16 v[12:15], v[36:39], v[32:35], v[12:15]
	ds_read_b128 v[36:39], v58 offset:21888
	ds_read_b128 v[52:55], v58 offset:21952
	s_waitcnt lgkmcnt(0)
	s_barrier
	v_mfma_f32_16x16x32_bf16 v[16:19], v[36:39], v[32:35], v[16:19]
	s_waitcnt vmcnt(2)
	ds_write_b128 v57, v[40:43]
	ds_write_b128 v57, v[20:23] offset:17408
	s_waitcnt vmcnt(1)
	ds_write_b128 v57, v[24:27] offset:8704
	s_waitcnt vmcnt(0)
	ds_write_b128 v57, v[28:31] offset:26112
	s_waitcnt lgkmcnt(0)
	s_barrier
	ds_read_b128 v[20:23], v58 offset:17408
	v_mfma_f32_16x16x32_bf16 v[12:15], v[48:51], v[44:47], v[12:15]
	ds_read_b128 v[24:27], v58 offset:21760
	ds_read_b128 v[28:31], v2
	ds_read_b128 v[32:35], v2 offset:64
	ds_read_b128 v[36:39], v58 offset:17472
	v_mfma_f32_16x16x32_bf16 v[16:19], v[52:55], v[44:47], v[16:19]
	s_waitcnt lgkmcnt(2)
	v_mfma_f32_16x16x32_bf16 v[12:15], v[20:23], v[28:31], v[12:15]
	global_load_dwordx4 v[20:23], v[8:9], off offset:768
	global_load_dwordx4 v[40:43], v[4:5], off offset:768
	ds_read_b128 v[44:47], v58 offset:21824
	v_mfma_f32_16x16x32_bf16 v[16:19], v[24:27], v[28:31], v[16:19]
	global_load_dwordx4 v[24:27], v[6:7], off offset:768
	global_load_dwordx4 v[28:31], v[10:11], off offset:768
	s_waitcnt lgkmcnt(1)
	v_mfma_f32_16x16x32_bf16 v[12:15], v[36:39], v[32:35], v[12:15]
	ds_read_b128 v[36:39], v58 offset:17536
	s_waitcnt lgkmcnt(1)
	v_mfma_f32_16x16x32_bf16 v[16:19], v[44:47], v[32:35], v[16:19]
	ds_read_b128 v[32:35], v2 offset:128
	ds_read_b128 v[44:47], v2 offset:192
	ds_read_b128 v[48:51], v58 offset:17600
	s_waitcnt lgkmcnt(2)
	v_mfma_f32_16x16x32_bf16 v[12:15], v[36:39], v[32:35], v[12:15]
	ds_read_b128 v[36:39], v58 offset:21888
	ds_read_b128 v[52:55], v58 offset:21952
	s_waitcnt lgkmcnt(0)
	s_barrier
; #define LAS __attribute__((address_space(3)))
; template <class Epi>
; __device__ __forceinline__ void gemm64_tile(LAS unsigned char* lds, const bf16_t* A, const bf16_t* Bt, const Epi& E) {
;     ...
;     for (int kt = 0; kt < NKT; ++kt) {
;         __syncthreads();
; #pragma unroll
;         for (int i = 0; i < 2; ++i) { *(LAS u32x4*)(As + (srow + 32 * i) * PITCH + sch * 16) = ra[i]; *(LAS u32x4*)(Bs + (srow + 32 * i) * PITCH + sch * 16) = rb[i]; }
;         __syncthreads();
;         if (kt + 1 < NKT) {
; #pragma unroll
;             for (int i = 0; i < 2; ++i) { ra[i] = *(const u32x4*)(ga + (size_t)(32 * i) * K + (kt + 1) * BK); rb[i] = *(const u32x4*)(gb + (size_t)(32 * i) * K + (kt + 1) * BK); }
;         }
; #pragma unroll
;         for (int ks = 0; ks < 4; ++ks) {
;             const bf16x8 Af = *(const LAS bf16x8*)(As + (16 * wr + fr) * PITCH + (32 * ks + 8 * fq) * 2);
; #pragma unroll
;             for (int n = 0; n < 2; ++n) {
;                 const bf16x8 Bf = *(const LAS bf16x8*)(Bs + (32 * wc + 16 * n + fr) * PITCH + (32 * ks + 8 * fq) * 2);
;                 acc[n] = __builtin_amdgcn_mfma_f32_16x16x32_bf16(Bf, Af, acc[n], 0, 0, 0);
;             }
;         }
	v_mfma_f32_16x16x32_bf16 v[16:19], v[36:39], v[32:35], v[16:19]
	s_waitcnt vmcnt(2)
	ds_write_b128 v57, v[40:43]
	ds_write_b128 v57, v[20:23] offset:17408
	s_waitcnt vmcnt(1)
	ds_write_b128 v57, v[24:27] offset:8704
	s_waitcnt vmcnt(0)
	ds_write_b128 v57, v[28:31] offset:26112
	s_waitcnt lgkmcnt(0)
	s_barrier
	ds_read_b128 v[20:23], v58 offset:17408
	v_mfma_f32_16x16x32_bf16 v[12:15], v[48:51], v[44:47], v[12:15]
	ds_read_b128 v[24:27], v58 offset:21760
	ds_read_b128 v[28:31], v2
	ds_read_b128 v[32:35], v2 offset:64
	ds_read_b128 v[36:39], v58 offset:17472
	v_mfma_f32_16x16x32_bf16 v[16:19], v[52:55], v[44:47], v[16:19]
	s_waitcnt lgkmcnt(2)
	v_mfma_f32_16x16x32_bf16 v[12:15], v[20:23], v[28:31], v[12:15]
	global_load_dwordx4 v[20:23], v[8:9], off offset:1024
	global_load_dwordx4 v[40:43], v[4:5], off offset:1024
	ds_read_b128 v[44:47], v58 offset:21824
	v_mfma_f32_16x16x32_bf16 v[16:19], v[24:27], v[28:31], v[16:19]
	global_load_dwordx4 v[24:27], v[6:7], off offset:1024
	global_load_dwordx4 v[28:31], v[10:11], off offset:1024
	s_waitcnt lgkmcnt(1)
	v_mfma_f32_16x16x32_bf16 v[12:15], v[36:39], v[32:35], v[12:15]
	ds_read_b128 v[36:39], v58 offset:17536
	s_waitcnt lgkmcnt(1)
	v_mfma_f32_16x16x32_bf16 v[16:19], v[44:47], v[32:35], v[16:19]
	ds_read_b128 v[32:35], v2 offset:128
	ds_read_b128 v[44:47], v2 offset:192
	ds_read_b128 v[48:51], v58 offset:17600
	s_waitcnt lgkmcnt(2)
	v_mfma_f32_16x16x32_bf16 v[12:15], v[36:39], v[32:35], v[12:15]
	ds_read_b128 v[36:39], v58 offset:21888
	ds_read_b128 v[52:55], v58 offset:21952
	s_waitcnt lgkmcnt(0)
	s_barrier
	v_mfma_f32_16x16x32_bf16 v[16:19], v[36:39], v[32:35], v[16:19]
	s_waitcnt vmcnt(2)
	ds_write_b128 v57, v[40:43]
	ds_write_b128 v57, v[20:23] offset:17408
	s_waitcnt vmcnt(1)
	ds_write_b128 v57, v[24:27] offset:8704
	s_waitcnt vmcnt(0)
	ds_write_b128 v57, v[28:31] offset:26112
	s_waitcnt lgkmcnt(0)
	s_barrier
	ds_read_b128 v[20:23], v58 offset:17408
	v_mfma_f32_16x16x32_bf16 v[12:15], v[48:51], v[44:47], v[12:15]
	ds_read_b128 v[24:27], v58 offset:21760
	ds_read_b128 v[28:31], v2
	ds_read_b128 v[32:35], v2 offset:64
	ds_read_b128 v[36:39], v58 offset:17472
	v_mfma_f32_16x16x32_bf16 v[16:19], v[52:55], v[44:47], v[16:19]
	s_waitcnt lgkmcnt(2)
	v_mfma_f32_16x16x32_bf16 v[12:15], v[20:23], v[28:31], v[12:15]
	global_load_dwordx4 v[20:23], v[8:9], off offset:1280
	global_load_dwordx4 v[40:43], v[4:5], off offset:1280
	ds_read_b128 v[44:47], v58 offset:21824
	v_mfma_f32_16x16x32_bf16 v[16:19], v[24:27], v[28:31], v[16:19]
	global_load_dwordx4 v[24:27], v[6:7], off offset:1280
	global_load_dwordx4 v[28:31], v[10:11], off offset:1280
	s_waitcnt lgkmcnt(1)
	v_mfma_f32_16x16x32_bf16 v[12:15], v[36:39], v[32:35], v[12:15]
	ds_read_b128 v[36:39], v58 offset:17536
	s_waitcnt lgkmcnt(1)
	v_mfma_f32_16x16x32_bf16 v[16:19], v[44:47], v[32:35], v[16:19]
	ds_read_b128 v[32:35], v2 offset:128
	ds_read_b128 v[44:47], v2 offset:192
	ds_read_b128 v[48:51], v58 offset:17600
	s_waitcnt lgkmcnt(2)
	v_mfma_f32_16x16x32_bf16 v[12:15], v[36:39], v[32:35], v[12:15]
	ds_read_b128 v[36:39], v58 offset:21888
	ds_read_b128 v[52:55], v58 offset:21952
	s_waitcnt lgkmcnt(0)
	s_barrier
	s_waitcnt vmcnt(2)
	ds_write_b128 v57, v[40:43]
	ds_write_b128 v57, v[20:23] offset:17408
	s_waitcnt vmcnt(1)
	ds_write_b128 v57, v[24:27] offset:8704
	s_waitcnt vmcnt(0)
	ds_write_b128 v57, v[28:31] offset:26112
	s_waitcnt lgkmcnt(0)
	s_barrier
	ds_read_b128 v[20:23], v58 offset:17408
	v_mfma_f32_16x16x32_bf16 v[16:19], v[36:39], v[32:35], v[16:19]
	ds_read_b128 v[24:27], v58 offset:21760
	ds_read_b128 v[28:31], v2
	ds_read_b128 v[32:35], v2 offset:64
	ds_read_b128 v[36:39], v58 offset:17472
	v_mfma_f32_16x16x32_bf16 v[12:15], v[48:51], v[44:47], v[12:15]
	v_mfma_f32_16x16x32_bf16 v[16:19], v[52:55], v[44:47], v[16:19]
	s_waitcnt lgkmcnt(2)
	v_mfma_f32_16x16x32_bf16 v[12:15], v[20:23], v[28:31], v[12:15]
	global_load_dwordx4 v[20:23], v[8:9], off offset:1536
	global_load_dwordx4 v[40:43], v[4:5], off offset:1536
	ds_read_b128 v[44:47], v58 offset:21824
	v_mfma_f32_16x16x32_bf16 v[16:19], v[24:27], v[28:31], v[16:19]
	global_load_dwordx4 v[24:27], v[6:7], off offset:1536
	global_load_dwordx4 v[28:31], v[10:11], off offset:1536
	s_waitcnt lgkmcnt(1)
	v_mfma_f32_16x16x32_bf16 v[12:15], v[36:39], v[32:35], v[12:15]
	ds_read_b128 v[36:39], v58 offset:17536
	s_waitcnt lgkmcnt(1)
	v_mfma_f32_16x16x32_bf16 v[16:19], v[44:47], v[32:35], v[16:19]
	ds_read_b128 v[32:35], v2 offset:128
	ds_read_b128 v[44:47], v2 offset:192
	ds_read_b128 v[48:51], v58 offset:17600
	s_waitcnt lgkmcnt(2)
	v_mfma_f32_16x16x32_bf16 v[12:15], v[36:39], v[32:35], v[12:15]
	ds_read_b128 v[36:39], v58 offset:21888
	ds_read_b128 v[52:55], v58 offset:21952
	s_waitcnt lgkmcnt(0)
	s_barrier
; #define LAS __attribute__((address_space(3)))
; __device__ __forceinline__ unsigned pk2(float lo, float hi) { f32x2 v = {lo, hi}; nbf2 r = __builtin_convertvector(v, nbf2); return __builtin_bit_cast(unsigned, r); }
; template <class Epi>
; __device__ __forceinline__ void gemm64_tile(LAS unsigned char* lds, const bf16_t* A, const bf16_t* Bt, const Epi& E) {
;     ...
;     for (int kt = 0; kt < NKT; ++kt) {
;         __syncthreads();
; #pragma unroll
;         for (int i = 0; i < 2; ++i) { *(LAS u32x4*)(As + (srow + 32 * i) * PITCH + sch * 16) = ra[i]; *(LAS u32x4*)(Bs + (srow + 32 * i) * PITCH + sch * 16) = rb[i]; }
;         __syncthreads();
;         if (kt + 1 < NKT) {
; #pragma unroll
;             for (int i = 0; i < 2; ++i) { ra[i] = *(const u32x4*)(ga + (size_t)(32 * i) * K + (kt + 1) * BK); rb[i] = *(const u32x4*)(gb + (size_t)(32 * i) * K + (kt + 1) * BK); }
;         }
; #pragma unroll
;         for (int ks = 0; ks < 4; ++ks) {
;             const bf16x8 Af = *(const LAS bf16x8*)(As + (16 * wr + fr) * PITCH + (32 * ks + 8 * fq) * 2);
; #pragma unroll
;             for (int n = 0; n < 2; ++n) {
;                 const bf16x8 Bf = *(const LAS bf16x8*)(Bs + (32 * wc + 16 * n + fr) * PITCH + (32 * ks + 8 * fq) * 2);
;                 acc[n] = __builtin_amdgcn_mfma_f32_16x16x32_bf16(Bf, Af, acc[n], 0, 0, 0);
;             }
;         }
;     }
;     __syncthreads();
;     E(acc, wr, wc, fr, fq, lds);
; }
;     __device__ __forceinline__ void operator()(f32x4 (&acc)[2], int wr, int wc, int fr, int fq, LAS unsigned char* lds) const {
; #pragma unroll
;         for (int n = 0; n < 2; ++n) { u32x2 w; w.x = pk2(acc[n][0], acc[n][1]); w.y = pk2(acc[n][2], acc[n][3]);
;             *(u32x2*)(O + (size_t)(16 * wr + fr) * ldc + 32 * wc + 16 * n + 4 * fq) = w; }
	s_waitcnt vmcnt(2)
	ds_write_b128 v57, v[40:43]
	ds_write_b128 v57, v[20:23] offset:17408
	s_waitcnt vmcnt(1)
	ds_write_b128 v57, v[24:27] offset:8704
	s_waitcnt vmcnt(0)
	ds_write_b128 v57, v[28:31] offset:26112
	s_waitcnt lgkmcnt(0)
	s_barrier
	ds_read_b128 v[20:23], v58 offset:17408
	v_mfma_f32_16x16x32_bf16 v[16:19], v[36:39], v[32:35], v[16:19]
	ds_read_b128 v[24:27], v58 offset:21760
	ds_read_b128 v[28:31], v2
	ds_read_b128 v[32:35], v2 offset:64
	ds_read_b128 v[36:39], v58 offset:17472
	v_mfma_f32_16x16x32_bf16 v[12:15], v[48:51], v[44:47], v[12:15]
	v_mfma_f32_16x16x32_bf16 v[16:19], v[52:55], v[44:47], v[16:19]
	s_waitcnt lgkmcnt(2)
	v_mfma_f32_16x16x32_bf16 v[12:15], v[20:23], v[28:31], v[12:15]
	global_load_dwordx4 v[20:23], v[8:9], off offset:1792
	global_load_dwordx4 v[40:43], v[4:5], off offset:1792
	ds_read_b128 v[44:47], v58 offset:21824
	v_mfma_f32_16x16x32_bf16 v[16:19], v[24:27], v[28:31], v[16:19]
	global_load_dwordx4 v[24:27], v[6:7], off offset:1792
	global_load_dwordx4 v[28:31], v[10:11], off offset:1792
	ds_read_b128 v[8:11], v58 offset:17536
	s_waitcnt lgkmcnt(2)
	v_mfma_f32_16x16x32_bf16 v[4:7], v[36:39], v[32:35], v[12:15]
	s_waitcnt lgkmcnt(1)
	v_mfma_f32_16x16x32_bf16 v[12:15], v[44:47], v[32:35], v[16:19]
	s_nop 2
	ds_read_b128 v[16:19], v2 offset:128
	ds_read_b128 v[32:35], v2 offset:192
	ds_read_b128 v[36:39], v58 offset:17600
	s_waitcnt lgkmcnt(2)
	v_mfma_f32_16x16x32_bf16 v[4:7], v[8:11], v[16:19], v[4:7]
	ds_read_b128 v[8:11], v58 offset:21888
	ds_read_b128 v[44:47], v58 offset:21952
	s_waitcnt lgkmcnt(0)
	s_barrier
	v_mfma_f32_16x16x32_bf16 v[8:11], v[8:11], v[16:19], v[12:15]
	s_waitcnt vmcnt(2)
	ds_write_b128 v57, v[40:43]
	ds_write_b128 v57, v[20:23] offset:17408
	s_waitcnt vmcnt(1)
	ds_write_b128 v57, v[24:27] offset:8704
	s_waitcnt vmcnt(0)
	ds_write_b128 v57, v[28:31] offset:26112
	s_waitcnt lgkmcnt(0)
	s_barrier
	ds_read_b128 v[12:15], v58 offset:17408
	v_mfma_f32_16x16x32_bf16 v[4:7], v[36:39], v[32:35], v[4:7]
	ds_read_b128 v[16:19], v2
	ds_read_b128 v[20:23], v2 offset:64
	ds_read_b128 v[24:27], v58 offset:17472
	v_mfma_f32_16x16x32_bf16 v[8:11], v[44:47], v[32:35], v[8:11]
	v_lshlrev_b64 v[32:33], 12, v[0:1]
	v_lshlrev_b32_e32 v0, 3, v56
	s_waitcnt lgkmcnt(2)
	v_mfma_f32_16x16x32_bf16 v[4:7], v[12:15], v[16:19], v[4:7]
	ds_read_b128 v[12:15], v58 offset:21760
	ds_read_b128 v[28:31], v58 offset:21824
	s_waitcnt lgkmcnt(1)
	v_mfma_f32_16x16x32_bf16 v[8:11], v[12:15], v[16:19], v[8:11]
	ds_read_b128 v[12:15], v58 offset:17536
	v_mfma_f32_16x16x32_bf16 v[4:7], v[24:27], v[20:23], v[4:7]
	ds_read_b128 v[16:19], v2 offset:128
	ds_read_b128 v[24:27], v58 offset:21888
	s_waitcnt lgkmcnt(3)
	v_mfma_f32_16x16x32_bf16 v[8:11], v[28:31], v[20:23], v[8:11]
	ds_read_b128 v[20:23], v2 offset:192
	ds_read_b128 v[28:31], v58 offset:17600
	s_waitcnt lgkmcnt(3)
	v_mfma_f32_16x16x32_bf16 v[2:5], v[12:15], v[16:19], v[4:7]
	ds_read_b128 v[12:15], v58 offset:21952
	s_waitcnt lgkmcnt(0)
	s_barrier
	v_mfma_f32_16x16x32_bf16 v[6:9], v[24:27], v[16:19], v[8:11]
	s_nop 2
	v_lshl_add_u64 v[10:11], s[2:3], 0, v[32:33]
	v_lshl_add_u64 v[10:11], v[10:11], 0, s[4:5]
	v_lshl_add_u64 v[10:11], v[10:11], 0, v[0:1]
	v_mfma_f32_16x16x32_bf16 v[0:3], v[28:31], v[20:23], v[2:5]
	v_mfma_f32_16x16x32_bf16 v[4:7], v[12:15], v[20:23], v[6:9]
	s_nop 6
	v_cvt_pk_bf16_f32 v0, v0, v1
	v_cvt_pk_bf16_f32 v1, v2, v3
	v_cvt_pk_bf16_f32 v2, v4, v5
	v_cvt_pk_bf16_f32 v3, v6, v7
	global_store_dwordx2 v[10:11], v[0:1], off
	global_store_dwordx2 v[10:11], v[2:3], off offset:32

; __global__ void __launch_bounds__(512, 2) fwd_megakernel(Args a) {
	.amdhsa_kernel _Z14fwd_megakernel4Args
		.amdhsa_group_segment_fixed_size 0
		.amdhsa_private_segment_fixed_size 0
		.amdhsa_kernarg_size 464
		.amdhsa_user_sgpr_count 2
		.amdhsa_user_sgpr_dispatch_ptr 0
		.amdhsa_user_sgpr_queue_ptr 0
		.amdhsa_user_sgpr_kernarg_segment_ptr 1
		.amdhsa_user_sgpr_dispatch_id 0
		.amdhsa_user_sgpr_kernarg_preload_length 0
		.amdhsa_user_sgpr_kernarg_preload_offset 0
		.amdhsa_user_sgpr_private_segment_size 0
		.amdhsa_uses_dynamic_stack 0
		.amdhsa_enable_private_segment 0
		.amdhsa_system_sgpr_workgroup_id_x 1
		.amdhsa_system_sgpr_workgroup_id_y 0
		.amdhsa_system_sgpr_workgroup_id_z 0
		.amdhsa_system_sgpr_workgroup_info 0
		.amdhsa_system_vgpr_workitem_id 2
		.amdhsa_next_free_vgpr 252
		.amdhsa_next_free_sgpr 102
		.amdhsa_accum_offset 252
		.amdhsa_reserve_vcc 1
		.amdhsa_float_round_mode_32 0
		.amdhsa_float_round_mode_16_64 0
		.amdhsa_float_denorm_mode_32 3
		.amdhsa_float_denorm_mode_16_64 3
		.amdhsa_dx10_clamp 1
		.amdhsa_ieee_mode 1
		.amdhsa_fp16_overflow 0
		.amdhsa_tg_split 0
		.amdhsa_exception_fp_ieee_invalid_op 0
		.amdhsa_exception_fp_denorm_src 0
		.amdhsa_exception_fp_ieee_div_zero 0
		.amdhsa_exception_fp_ieee_overflow 0
		.amdhsa_exception_fp_ieee_underflow 0
		.amdhsa_exception_fp_ieee_inexact 0
		.amdhsa_exception_int_div_zero 0
	.end_amdhsa_kernel

; __global__ void __launch_bounds__(512, 2) fwd_megakernel(Args a) {
amdhsa.kernels:
  - .agpr_count:     0
    .args:
      - .offset:         0
        .size:           208
        .value_kind:     by_value
      - .offset:         208
        .size:           4
        .value_kind:     hidden_block_count_x
      - .offset:         212
        .size:           4
        .value_kind:     hidden_block_count_y
      - .offset:         216
        .size:           4
        .value_kind:     hidden_block_count_z
      - .offset:         220
        .size:           2
        .value_kind:     hidden_group_size_x
      - .offset:         222
        .size:           2
        .value_kind:     hidden_group_size_y
      - .offset:         224
        .size:           2
        .value_kind:     hidden_group_size_z
      - .offset:         226
        .size:           2
        .value_kind:     hidden_remainder_x
      - .offset:         228
        .size:           2
        .value_kind:     hidden_remainder_y
      - .offset:         230
        .size:           2
        .value_kind:     hidden_remainder_z
      - .offset:         248
        .size:           8
        .value_kind:     hidden_global_offset_x
      - .offset:         256
        .size:           8
        .value_kind:     hidden_global_offset_y
      - .offset:         264
        .size:           8
        .value_kind:     hidden_global_offset_z
      - .offset:         272
        .size:           2
        .value_kind:     hidden_grid_dims
      - .offset:         296
        .size:           8
        .value_kind:     hidden_multigrid_sync_arg
      - .offset:         328
        .size:           4
        .value_kind:     hidden_dynamic_lds_size
    .group_segment_fixed_size: 0
    .kernarg_segment_align: 8
    .kernarg_segment_size: 464
    .language:       OpenCL C
    .language_version:
      - 2
      - 0
    .max_flat_workgroup_size: 512
    .name:           _Z14fwd_megakernel4Args
    .private_segment_fixed_size: 0
    .sgpr_count:     108
    .sgpr_spill_count: 0
    .symbol:         _Z14fwd_megakernel4Args.kd
    .uniform_work_group_size: 1
    .uses_dynamic_stack: false
    .vgpr_count:     252
    .vgpr_spill_count: 0
    .wavefront_size: 64
